# ffn_up phase: one static s_setprio 1 for waves 4-7 at phase entry (reset at the phase barrier)
# baseline (speedup 1.0000x reference)
; template <int AMODE, bool SWAPO = true>
; DI void mainloop_dma16(f32x4 (&acc)[4][2][2][2], const TD& c, const TD& n, bool hasn, bool primed, int& s, int tid) {
;     ...
;     auto offs = [&](const TD& t, int (&ao)[4], int (&bo)[C::NBI]) {
; #pragma unroll
;         for (int i = 0; i < 4; ++i) {
;             int row = t.arow0 + (4 * w + i) * 8 + (l >> 3); row = row < 0 ? 0 : (row > t.amax ? t.amax : row);
;             ao[i] = row * t.lda + ((l & 7) ^ (((l >> 4) + 4 * (i & 1)) & 7)) * 8;
;         }
; #pragma unroll
;         for (int i = 0; i < C::NBI; ++i) {
;             const int row = t.brow0 + (C::NBI * w + i) * 8 + (l >> 3);
;             bo[i] = row * t.ldb + ((l & 7) ^ (((l >> 4) + 4 * (i & 1)) & 7)) * 8;
;         }
;     };
;     (void)dry;
;     constexpr int MI = 4; typedef Cfg<MI> C;
;     const bf16_t* Xb = (const bf16_t*)(P.ws + OFF_XB); const bf16_t* W = (const bf16_t*)(P.ws + OFF_WB) + WB_FFN + L * W_FFN_SZ + W_FFN_UP;
;     bf16_t* GT = (bf16_t*)(P.ws + OFF_GATED);
;     const float* cw = P.ffn_conv_w + (size_t)L * 3 * 5632; const float* cb = P.ffn_conv_b + (size_t)L * 5632;
;     float* xch = (float*)(smem + XCH_OFF);
;     constexpr int NT = 5632 / C::BN, MT = (TT + 253) / 254;
;     constexpr int PW = 8;
;     auto tmap = [&](int lin, int& mt, int& nt) { const int panel = lin / (MT * PW), within = lin - panel * (MT * PW), pw = (NT - panel * PW) < PW ? (NT - panel * PW) : PW; mt = within / pw; nt = panel * PW + within % pw; };
;     auto td = [&](int lin) { int mt, nt; tmap(lin, mt, nt); return mk_td(Xb, DM, mt * 254 - 2, TT - 1, W, 1024, nt * C::BN, 16); };
;     constexpr int NTILES_ = MT * NT; int stg = 0; bool primed = false;
;     for (int tile = vb; tile < MT * NT; tile += nb) {
;         int mt, nt; tmap(tile, mt, nt);
;         f32x4 acc[MI][2][2][2];
;         { const TD c_ = td(tile); const bool hn_ = tile + nb < NTILES_; const TD n_ = td(hn_ ? tile + nb : tile); mainloop_dma16<0, false>(acc, c_, n_, hn_, primed, stg, tid); primed = hn_; }
.LBB0_1186:
	s_andn2_b64 vcc, exec, s[0:1]
	s_cbranch_vccnz .LBB0_1731
	v_readfirstlane_b32 s98, v249
	s_nop 3
	s_cmp_ge_u32 s98, 0x100
	s_cbranch_scc0 .Lfup_noprio
	s_setprio 1
.Lfup_noprio:
	v_mov_b32_e32 v178, v249
	v_readlane_b32 s26, v253, 0
	s_cmpk_gt_i32 s26, 0xb2b
	s_cbranch_scc1 .LBB0_1664
	s_mul_i32 s1, s60, 0x1080000
	v_readlane_b32 s4, v254, 48
	s_mul_hi_u32 s0, s60, 0x1080000
	s_add_u32 s8, s4, s1
	v_readlane_b32 s1, v254, 49
	v_readlane_b32 s40, v255, 30
	v_ashrrev_i32_e32 v0, 6, v178
	s_addc_u32 s9, s1, s0
	s_mul_i32 s1, s60, 0x10800
	v_readlane_b32 s41, v255, 31
	v_readlane_b32 s42, v255, 32
	v_readlane_b32 s43, v255, 33
	s_waitcnt lgkmcnt(0)
	v_lshrrev_b32_e32 v1, 30, v0
	v_writelane_b32 v255, s53, 47
	s_mul_hi_u32 s0, s60, 0x10800
	s_add_u32 s58, s40, s1
	v_add_u32_e32 v1, v0, v1
	v_writelane_b32 v255, s74, 48
	s_addc_u32 s59, s41, s0
	s_mul_i32 s1, s60, 0x5800
	v_and_b32_e32 v2, 0x7fffc, v1
	v_lshlrev_b32_e32 v5, 7, v178
	v_lshlrev_b32_e32 v1, 12, v1
	v_writelane_b32 v255, s75, 49
	s_mul_hi_u32 s0, s60, 0x5800
	s_add_u32 s14, s42, s1
	v_lshrrev_b32_e32 v3, 1, v178
	v_and_b32_e32 v179, 0x780, v5
	v_bfe_u32 v5, v178, 4, 2
	v_and_b32_e32 v180, 0xffffc000, v1
	v_bfe_u32 v1, v178, 3, 3
	v_writelane_b32 v255, s54, 50
	s_addc_u32 s15, s43, s0
	v_sub_u32_e32 v2, v0, v2
	v_bfe_u32 v4, v178, 1, 3
	v_lshl_or_b32 v182, v0, 5, v1
	v_xor_b32_e32 v1, v5, v178
	v_lshl_add_u32 v188, v0, 12, 16
	v_bitop3_b32 v0, v5, v3, 7 bitop3:0x78
	v_writelane_b32 v255, s55, 51
	v_lshlrev_b32_e32 v1, 3, v1
	v_lshlrev_b32_e32 v189, 4, v0
	v_bitop3_b32 v0, v5, v4, 4 bitop3:0x36
	v_writelane_b32 v255, s14, 52
	v_lshlrev_b32_e32 v181, 13, v2
	v_and_b32_e32 v183, 56, v1
	v_or_b32_e32 v184, 8, v182
	v_bitop3_b32 v185, v1, 32, 56 bitop3:0x6c
	v_or_b32_e32 v186, 16, v182
	v_or_b32_e32 v187, 24, v182
	v_lshlrev_b32_e32 v190, 4, v0
	s_mov_b32 s28, 0
	s_mov_b64 s[0:1], 0
	v_writelane_b32 v255, s15, 53
	s_branch .LBB0_1190

; DI void xcd_barrier(const XcdBarrier& b) {
;     asm volatile("s_waitcnt vmcnt(0)" ::: "memory");
;     __syncthreads();
;     if (threadIdx.x == 0) {
;         unsigned* bar = b.bar;
;         __builtin_amdgcn_s_waitcnt(0);
;         unsigned nloc = b.st[0], nx = b.st[1];
;         if (nloc == 0u) { xcd_barrier_complete(bar, b.x, nloc, nx); b.st[0] = nloc; b.st[1] = nx; }
.LBB0_1664:
	v_readlane_b32 s0, v253, 3
	s_add_i32 s40, s53, 2
	v_readlane_b32 s1, v253, 4
	s_cmp_ge_i32 s40, s1
	s_cbranch_scc1 .LBB0_1731
	v_readlane_b32 s0, v255, 46
	s_cmp_lg_u32 s0, 0
	s_cbranch_scc0 .LBB0_1677
	s_setprio 0
	s_waitcnt vmcnt(0)
	s_waitcnt vmcnt(0) lgkmcnt(0)
	s_barrier
	s_mov_b64 s[0:1], exec
	v_readlane_b32 s4, v253, 5
	v_readlane_b32 s5, v253, 6
	s_and_b64 s[4:5], s[0:1], s[4:5]
	s_mov_b64 exec, s[4:5]
	s_cbranch_execz .LBB0_1719
	s_waitcnt vmcnt(0) expcnt(0) lgkmcnt(0)
	ds_read_b32 v2, v177
	ds_read_b32 v0, v177 offset:4
	s_waitcnt lgkmcnt(1)
	v_cmp_ne_u32_e32 vcc, 0, v2
	s_cbranch_vccnz .LBB0_1683
	s_mov_b32 s20, 1
	s_branch .LBB0_1670
